# h7 + attention bias adds as scalar v_add_f32 (swapped ds_read2 offsets) instead of v_pk_add_f32 on MFMA results, DA and dilated loops
# speedup vs baseline: 1.0073x; 1.0021x over previous
; #define LAS __attribute__((address_space(3)))
; #define GAS __attribute__((address_space(1)))
; template <int MODE> ...
;     ...
;         if (more) {
;             const int kv1 = 64 * (kt + 1);
;             kr0 = *(const GAS u32x4*)(ksrc + (tok0 + (size_t)(kv1 + kp_row0) * dil) * 2048);
;             kr1 = *(const GAS u32x4*)(ksrc + (tok0 + (size_t)(kv1 + kp_row0 + 32) * dil) * 2048);
;             vr0 = *(const GAS u32x4*)(vsrc + kv1);
;             vr1 = *(const GAS u32x4*)(vsrc + (size_t)64 * TOK + kv1);
;             asm volatile("" ::: "memory");
;         }
;         const int kv0 = 64 * kt;
;         bool skip = kv0 > q_lo + 31;
;         if (MODE == 1) skip = skip || (kv0 + 63 < q_lo - 128);
;         if (!skip) {
;             const LAS unsigned char* kb = lds + bufsel * AT_BUF; const LAS unsigned char* vb = kb + AT_KBYTES;
;             f32x16 s0, s1;
; #pragma unroll
;             for (int r = 0; r < 16; ++r) { s0[r] = 0.f; s1[r] = 0.f; }
;             {
;                 bf16x8 ka[4], kc[4];
; #pragma unroll
;                 for (int ds = 0; ds < 4; ++ds) {
;                     ka[ds] = *(const LAS bf16x8*)(kb + r32 * AT_KROW + mp * 128 + (16 * ds + 8 * hi) * 2);
;                     kc[ds] = *(const LAS bf16x8*)(kb + (32 + r32) * AT_KROW + mp * 128 + (16 * ds + 8 * hi) * 2);
;                 }
;                 __builtin_amdgcn_sched_barrier(0);
; #pragma unroll
;                 for (int ds = 0; ds < 4; ++ds) {
;                     s0 = __builtin_amdgcn_mfma_f32_32x32x16_bf16(ka[ds], qf[ds], s0, 0, 0, 0);
;                     s1 = __builtin_amdgcn_mfma_f32_32x32x16_bf16(kc[ds], qf[ds], s1, 0, 0, 0);
;                 }
;             }
;             const int relbase = qi - kv0 - 4 * hi;
;             constexpr int cmax = (MODE == 0) ? 2047 : 128;
;             float mx = -1e30f;
;             bool interior = (kv0 + 63 <= q_lo);
;             if (MODE == 1) interior = interior && (q_lo + 31 - kv0 <= 128);
;             if (interior) {
;                 const LAS float* p = biasL + mp * 2048 + (relbase - 59);
; #pragma unroll
;                 for (int r = 0; r < 16; ++r) {
;                     const int o = 59 - ((r & 3) + 8 * (r >> 2));
;                     s0[r] += p[o]; s1[r] += p[o - 32];
;                     mx = fmaxf(mx, fmaxf(s0[r], s1[r]));
;                 }
.LBB0_381:
	v_lshl_add_u64 v[2:3], s[54:55], 0, v[144:145]
	v_add_co_u32_e32 v4, vcc, s90, v2
	v_lshl_add_u64 v[10:11], s[54:55], 0, v[142:143]
	s_nop 0
	v_addc_co_u32_e32 v5, vcc, 0, v3, vcc
	v_add_co_u32_e32 v6, vcc, s91, v2
	s_waitcnt lgkmcnt(0)
	s_nop 0
	v_addc_co_u32_e32 v7, vcc, 0, v3, vcc
	v_add_co_u32_e32 v12, vcc, 0x20000000, v10
	s_barrier
	s_nop 0
	v_addc_co_u32_e32 v13, vcc, 0, v11, vcc
	v_add_co_u32_e32 v14, vcc, 0x20800000, v10
	global_load_dwordx4 v[2:5], v[4:5], off offset:2048
	s_nop 0
	global_load_dwordx4 v[6:9], v[6:7], off offset:2048
	v_addc_co_u32_e32 v15, vcc, 0, v11, vcc
	global_load_dwordx4 v[10:13], v[12:13], off offset:128
	s_nop 0
	global_load_dwordx4 v[128:131], v[14:15], off offset:128
	s_and_b32 s29, s25, 1
	s_add_i32 s28, s14, 64
	s_cmp_gt_u32 s28, s26
	s_cbranch_scc1 .LBB0_387
	s_mul_i32 s15, s29, 0x8800
	s_add_i32 s30, s15, 0
	s_add_i32 s15, s27, s30
	v_add3_u32 v0, s15, v197, v136
	ds_read_b128 v[80:83], v0
	ds_read_b128 v[148:151], v0 offset:32
	ds_read_b128 v[84:87], v0 offset:8704
	ds_read_b128 v[152:155], v0 offset:8736
	ds_read_b128 v[156:159], v0 offset:64
	ds_read_b128 v[160:163], v0 offset:96
	ds_read_b128 v[164:167], v0 offset:8768
	ds_read_b128 v[168:171], v0 offset:8800
	ds_read2_b32 v[14:15], v200 offset0:59 offset1:58
	ds_read2_b32 v[218:219], v200 offset0:27 offset1:26
	ds_read2_b32 v[220:221], v200 offset0:25 offset1:24
	ds_read2_b32 v[222:223], v200 offset0:57 offset1:56
	ds_read2_b32 v[224:225], v200 offset0:51 offset1:50
	ds_read2_b32 v[174:175], v200 offset0:19 offset1:18
	ds_read2_b32 v[226:227], v200 offset0:49 offset1:48
	s_waitcnt lgkmcnt(14)
	v_mfma_f32_32x32x16_bf16 v[96:111], v[80:83], v[124:127], 0
	s_add_i32 s31, s14, 0x7f
	s_mov_b64 s[14:15], -1
	s_cmp_gt_u32 s31, s24
	ds_read2_b32 v[172:173], v200 offset0:17 offset1:16
	s_waitcnt lgkmcnt(13)
	v_mfma_f32_32x32x16_bf16 v[80:95], v[84:87], v[124:127], 0
	v_mfma_f32_32x32x16_bf16 v[96:111], v[148:151], v[120:123], v[96:111]
	ds_read2_b32 v[242:243], v200 offset0:43 offset1:42
	ds_read2_b32 v[182:183], v200 offset0:11 offset1:10
	s_waitcnt lgkmcnt(14)
	v_mfma_f32_32x32x16_bf16 v[80:95], v[152:155], v[120:123], v[80:95]
	ds_read2_b32 v[176:177], v200 offset0:41 offset1:40
	s_waitcnt lgkmcnt(14)
	v_mfma_f32_32x32x16_bf16 v[96:111], v[156:159], v[116:119], v[96:111]
	ds_read2_b32 v[184:185], v200 offset0:9 offset1:8
	s_waitcnt lgkmcnt(13)
	v_mfma_f32_32x32x16_bf16 v[80:95], v[164:167], v[116:119], v[80:95]
	v_mfma_f32_32x32x16_bf16 v[96:111], v[160:163], v[112:115], v[96:111]
	ds_read2_b32 v[180:181], v200 offset0:35 offset1:34
	ds_read2_b32 v[188:189], v200 offset0:3 offset1:2
	s_waitcnt lgkmcnt(14)
	v_mfma_f32_32x32x16_bf16 v[80:95], v[168:171], v[112:115], v[80:95]
	ds_read2_b32 v[178:179], v200 offset0:33 offset1:32
	s_nop 11
	s_cbranch_scc1 .LdaA_bias_masked
	s_waitcnt lgkmcnt(14)
	v_add_f32_e32 v14, v96, v14
	v_add_f32_e32 v15, v97, v15
	ds_read2_b32 v[186:187], v200 offset0:1 offset1:0
	s_waitcnt lgkmcnt(14)
	v_add_f32_e32 v166, v80, v218
	v_add_f32_e32 v167, v81, v219
	s_waitcnt lgkmcnt(13)
	v_add_f32_e32 v168, v82, v220
	v_add_f32_e32 v169, v83, v221
	s_waitcnt lgkmcnt(12)
	v_add_f32_e32 v148, v98, v222
	v_add_f32_e32 v149, v99, v223
	s_waitcnt lgkmcnt(11)
	v_add_f32_e32 v152, v100, v224
	v_add_f32_e32 v153, v101, v225
	s_waitcnt lgkmcnt(10)
	v_add_f32_e32 v174, v84, v174
	v_add_f32_e32 v175, v85, v175
	s_waitcnt lgkmcnt(9)
	v_add_f32_e32 v150, v102, v226
	v_add_f32_e32 v151, v103, v227
	s_waitcnt lgkmcnt(8)
	v_add_f32_e32 v172, v86, v172
	v_add_f32_e32 v173, v87, v173
	s_waitcnt lgkmcnt(7)
	v_add_f32_e32 v170, v104, v242
	v_add_f32_e32 v171, v105, v243
	s_waitcnt lgkmcnt(6)
	v_add_f32_e32 v182, v88, v182
	v_add_f32_e32 v183, v89, v183
	s_waitcnt lgkmcnt(5)
	v_add_f32_e32 v176, v106, v176
	v_add_f32_e32 v177, v107, v177
	s_waitcnt lgkmcnt(4)
	v_add_f32_e32 v184, v90, v184
	v_add_f32_e32 v185, v91, v185
	s_waitcnt lgkmcnt(3)
	v_add_f32_e32 v180, v108, v180
	v_add_f32_e32 v181, v109, v181
	s_waitcnt lgkmcnt(2)
	v_add_f32_e32 v188, v92, v188
	v_add_f32_e32 v189, v93, v189
	s_waitcnt lgkmcnt(1)
	v_add_f32_e32 v178, v110, v178
	v_add_f32_e32 v179, v111, v179
	s_waitcnt lgkmcnt(0)
	v_add_f32_e32 v186, v94, v186
	v_add_f32_e32 v187, v95, v187
	v_max_f32_e32 v80, v14, v166
	v_max_f32_e32 v81, v15, v167
	v_max3_f32 v82, v80, s84, v81
	v_max_f32_e32 v80, v168, v148
	v_max_f32_e32 v81, v169, v149
	v_max3_f32 v82, v82, v80, v81
	v_max_f32_e32 v80, v152, v174
	v_max_f32_e32 v81, v153, v175
	v_max3_f32 v82, v82, v80, v81
	v_max_f32_e32 v80, v150, v172
	v_max_f32_e32 v81, v151, v173
	v_max3_f32 v82, v82, v80, v81
	v_max_f32_e32 v80, v170, v182
	v_max_f32_e32 v81, v171, v183
	v_max3_f32 v82, v82, v80, v81
	v_max_f32_e32 v80, v176, v184
	v_max_f32_e32 v81, v177, v185
	v_max3_f32 v82, v82, v80, v81
	v_max_f32_e32 v80, v180, v188
	v_max_f32_e32 v81, v181, v189
	v_max3_f32 v82, v82, v80, v81
	v_max_f32_e32 v80, v178, v186
	v_max_f32_e32 v81, v179, v187
	v_max3_f32 v0, v82, v80, v81
	s_branch .LBB0_386
; #define LAS __attribute__((address_space(3)))
; __device__ __forceinline__ float max_x32(float v) { auto rr = __builtin_amdgcn_permlane32_swap(__float_as_uint(v), __float_as_uint(v), false, false); return fmaxf(__uint_as_float(rr[0]), __uint_as_float(rr[1])); }
; template <int MODE> ...
;     ...
;                 const volatile LAS float* bl = (const volatile LAS float*)(biasL + mp * 2048);
;                 float bb0[16], bb1[16];
; #pragma unroll
;                 for (int r = 0; r < 16; ++r) {
;                     const int rel0 = relbase - ((r & 3) + 8 * (r >> 2));
;                     bb0[r] = bl[min(max(rel0, 0), cmax)]; bb1[r] = bl[min(max(rel0 - 32, 0), cmax)];
;                 }
; #pragma unroll
;                 for (int r = 0; r < 16; ++r) {
;                     const int rel0 = relbase - ((r & 3) + 8 * (r >> 2)), rel1 = rel0 - 32;
;                     bool ok0 = rel0 >= 0, ok1 = rel1 >= 0;
;                     if (MODE == 1) { ok0 = ok0 && (rel0 <= 128); ok1 = ok1 && (rel1 <= 128); }
;                     const float t0 = s0[r] + bb0[r], t1 = s1[r] + bb1[r];
;                     s0[r] = ok0 ? t0 : -1e30f; s1[r] = ok1 ? t1 : -1e30f;
;                     mx = fmaxf(mx, fmaxf(s0[r], s1[r]));
;                 }
;             }
;             mx = max_x32(mx);
.LdaA_bias_masked:
	v_add_u32_e32 v0, s33, v199
	s_waitcnt lgkmcnt(14)
	v_add_f32_e32 v14, v96, v14
	v_add_f32_e32 v15, v97, v15
	ds_read2_b32 v[186:187], v200 offset0:1 offset1:0
	v_cmp_lt_i32_e32 vcc, -1, v0
	v_cmp_lt_i32_e64 s[100:101], 0, v0
	s_nop 1
	v_cndmask_b32_e32 v14, v214, v14, vcc
	v_cndmask_b32_e64 v15, v214, v15, s[100:101]
	s_waitcnt lgkmcnt(14)
	v_add_f32_e32 v166, v80, v218
	v_add_f32_e32 v167, v81, v219
	v_cmp_lt_i32_e32 vcc, 31, v0
	v_cmp_lt_i32_e64 s[100:101], 32, v0
	s_nop 1
	v_cndmask_b32_e32 v166, v214, v166, vcc
	v_cndmask_b32_e64 v167, v214, v167, s[100:101]
	s_waitcnt lgkmcnt(13)
	v_add_f32_e32 v168, v82, v220
	v_add_f32_e32 v169, v83, v221
	v_cmp_lt_i32_e32 vcc, 33, v0
	v_cmp_lt_i32_e64 s[100:101], 34, v0
	s_nop 1
	v_cndmask_b32_e32 v168, v214, v168, vcc
	v_cndmask_b32_e64 v169, v214, v169, s[100:101]
	s_waitcnt lgkmcnt(12)
	v_add_f32_e32 v148, v98, v222
	v_add_f32_e32 v149, v99, v223
	v_cmp_lt_i32_e32 vcc, 1, v0
	v_cmp_lt_i32_e64 s[100:101], 2, v0
	s_nop 1
	v_cndmask_b32_e32 v148, v214, v148, vcc
	v_cndmask_b32_e64 v149, v214, v149, s[100:101]
	s_waitcnt lgkmcnt(11)
	v_add_f32_e32 v152, v100, v224
	v_add_f32_e32 v153, v101, v225
	v_cmp_lt_i32_e32 vcc, 7, v0
	v_cmp_lt_i32_e64 s[100:101], 8, v0
	s_nop 1
	v_cndmask_b32_e32 v152, v214, v152, vcc
	v_cndmask_b32_e64 v153, v214, v153, s[100:101]
	s_waitcnt lgkmcnt(10)
	v_add_f32_e32 v174, v84, v174
	v_add_f32_e32 v175, v85, v175
	v_cmp_lt_i32_e32 vcc, 39, v0
	v_cmp_lt_i32_e64 s[100:101], 40, v0
	s_nop 1
	v_cndmask_b32_e32 v174, v214, v174, vcc
	v_cndmask_b32_e64 v175, v214, v175, s[100:101]
	s_waitcnt lgkmcnt(9)
	v_add_f32_e32 v150, v102, v226
	v_add_f32_e32 v151, v103, v227
	v_cmp_lt_i32_e32 vcc, 9, v0
	v_cmp_lt_i32_e64 s[100:101], 10, v0
	s_nop 1
	v_cndmask_b32_e32 v150, v214, v150, vcc
	v_cndmask_b32_e64 v151, v214, v151, s[100:101]
	s_waitcnt lgkmcnt(8)
	v_add_f32_e32 v172, v86, v172
	v_add_f32_e32 v173, v87, v173
	v_cmp_lt_i32_e32 vcc, 41, v0
	v_cmp_lt_i32_e64 s[100:101], 42, v0
	s_nop 1
	v_cndmask_b32_e32 v172, v214, v172, vcc
	v_cndmask_b32_e64 v173, v214, v173, s[100:101]
	s_waitcnt lgkmcnt(7)
	v_add_f32_e32 v170, v104, v242
	v_add_f32_e32 v171, v105, v243
	v_cmp_lt_i32_e32 vcc, 15, v0
	v_cmp_lt_i32_e64 s[100:101], 16, v0
	s_nop 1
	v_cndmask_b32_e32 v170, v214, v170, vcc
	v_cndmask_b32_e64 v171, v214, v171, s[100:101]
	s_waitcnt lgkmcnt(6)
	v_add_f32_e32 v182, v88, v182
	v_add_f32_e32 v183, v89, v183
	v_cmp_lt_i32_e32 vcc, 47, v0
	v_cmp_lt_i32_e64 s[100:101], 48, v0
	s_nop 1
	v_cndmask_b32_e32 v182, v214, v182, vcc
	v_cndmask_b32_e64 v183, v214, v183, s[100:101]
	s_waitcnt lgkmcnt(5)
	v_add_f32_e32 v176, v106, v176
	v_add_f32_e32 v177, v107, v177
	v_cmp_lt_i32_e32 vcc, 17, v0
	v_cmp_lt_i32_e64 s[100:101], 18, v0
	s_nop 1
	v_cndmask_b32_e32 v176, v214, v176, vcc
	v_cndmask_b32_e64 v177, v214, v177, s[100:101]
	s_waitcnt lgkmcnt(4)
	v_add_f32_e32 v184, v90, v184
	v_add_f32_e32 v185, v91, v185
	v_cmp_lt_i32_e32 vcc, 49, v0
	v_cmp_lt_i32_e64 s[100:101], 50, v0
	s_nop 1
	v_cndmask_b32_e32 v184, v214, v184, vcc
	v_cndmask_b32_e64 v185, v214, v185, s[100:101]
	s_waitcnt lgkmcnt(3)
	v_add_f32_e32 v180, v108, v180
	v_add_f32_e32 v181, v109, v181
	v_cmp_lt_i32_e32 vcc, 23, v0
	v_cmp_lt_i32_e64 s[100:101], 24, v0
	s_nop 1
	v_cndmask_b32_e32 v180, v214, v180, vcc
	v_cndmask_b32_e64 v181, v214, v181, s[100:101]
	s_waitcnt lgkmcnt(2)
	v_add_f32_e32 v188, v92, v188
	v_add_f32_e32 v189, v93, v189
	v_cmp_lt_i32_e32 vcc, 55, v0
	v_cmp_lt_i32_e64 s[100:101], 56, v0
	s_nop 1
	v_cndmask_b32_e32 v188, v214, v188, vcc
	v_cndmask_b32_e64 v189, v214, v189, s[100:101]
	s_waitcnt lgkmcnt(1)
	v_add_f32_e32 v178, v110, v178
	v_add_f32_e32 v179, v111, v179
	v_cmp_lt_i32_e32 vcc, 25, v0
	v_cmp_lt_i32_e64 s[100:101], 26, v0
	s_nop 1
	v_cndmask_b32_e32 v178, v214, v178, vcc
	v_cndmask_b32_e64 v179, v214, v179, s[100:101]
	s_waitcnt lgkmcnt(0)
	v_add_f32_e32 v186, v94, v186
	v_add_f32_e32 v187, v95, v187
	v_cmp_lt_i32_e32 vcc, 57, v0
	v_cmp_lt_i32_e64 s[100:101], 58, v0
	s_nop 1
	v_cndmask_b32_e32 v186, v214, v186, vcc
	v_cndmask_b32_e64 v187, v214, v187, s[100:101]
	v_max_f32_e32 v80, v14, v166
	v_max_f32_e32 v81, v15, v167
	v_max3_f32 v82, v80, s84, v81
	v_max_f32_e32 v80, v168, v148
	v_max_f32_e32 v81, v169, v149
	v_max3_f32 v82, v82, v80, v81
	v_max_f32_e32 v80, v152, v174
	v_max_f32_e32 v81, v153, v175
	v_max3_f32 v82, v82, v80, v81
	v_max_f32_e32 v80, v150, v172
	v_max_f32_e32 v81, v151, v173
	v_max3_f32 v82, v82, v80, v81
	v_max_f32_e32 v80, v170, v182
	v_max_f32_e32 v81, v171, v183
	v_max3_f32 v82, v82, v80, v81
	v_max_f32_e32 v80, v176, v184
	v_max_f32_e32 v81, v177, v185
	v_max3_f32 v82, v82, v80, v81
	v_max_f32_e32 v80, v180, v188
	v_max_f32_e32 v81, v181, v189
	v_max3_f32 v82, v82, v80, v81
	v_max_f32_e32 v80, v178, v186
	v_max_f32_e32 v81, v179, v187
	v_max3_f32 v0, v82, v80, v81

; #define LAS __attribute__((address_space(3)))
; #define GAS __attribute__((address_space(1)))
; template <int MODE> ...
;     ...
;         if (more) {
;             const int kv1 = 64 * (kt + 1);
;             kr0 = *(const GAS u32x4*)(ksrc + (tok0 + (size_t)(kv1 + kp_row0) * dil) * 2048);
;             kr1 = *(const GAS u32x4*)(ksrc + (tok0 + (size_t)(kv1 + kp_row0 + 32) * dil) * 2048);
;             vr0 = *(const GAS u32x4*)(vsrc + kv1);
;             vr1 = *(const GAS u32x4*)(vsrc + (size_t)64 * TOK + kv1);
;             asm volatile("" ::: "memory");
;         }
;         const int kv0 = 64 * kt;
;         bool skip = kv0 > q_lo + 31;
;         if (MODE == 1) skip = skip || (kv0 + 63 < q_lo - 128);
;         if (!skip) {
;             const LAS unsigned char* kb = lds + bufsel * AT_BUF; const LAS unsigned char* vb = kb + AT_KBYTES;
;             f32x16 s0, s1;
; #pragma unroll
;             for (int r = 0; r < 16; ++r) { s0[r] = 0.f; s1[r] = 0.f; }
;             {
;                 bf16x8 ka[4], kc[4];
; #pragma unroll
;                 for (int ds = 0; ds < 4; ++ds) {
;                     ka[ds] = *(const LAS bf16x8*)(kb + r32 * AT_KROW + mp * 128 + (16 * ds + 8 * hi) * 2);
;                     kc[ds] = *(const LAS bf16x8*)(kb + (32 + r32) * AT_KROW + mp * 128 + (16 * ds + 8 * hi) * 2);
;                 }
;                 __builtin_amdgcn_sched_barrier(0);
; #pragma unroll
;                 for (int ds = 0; ds < 4; ++ds) {
;                     s0 = __builtin_amdgcn_mfma_f32_32x32x16_bf16(ka[ds], qf[ds], s0, 0, 0, 0);
;                     s1 = __builtin_amdgcn_mfma_f32_32x32x16_bf16(kc[ds], qf[ds], s1, 0, 0, 0);
;                 }
;             }
;             const int relbase = qi - kv0 - 4 * hi;
;             constexpr int cmax = (MODE == 0) ? 2047 : 128;
;             float mx = -1e30f;
;             bool interior = (kv0 + 63 <= q_lo);
;             if (MODE == 1) interior = interior && (q_lo + 31 - kv0 <= 128);
;             if (interior) {
;                 const LAS float* p = biasL + mp * 2048 + (relbase - 59);
; #pragma unroll
;                 for (int r = 0; r < 16; ++r) {
;                     const int o = 59 - ((r & 3) + 8 * (r >> 2));
;                     s0[r] += p[o]; s1[r] += p[o - 32];
;                     mx = fmaxf(mx, fmaxf(s0[r], s1[r]));
;                 }
.LBB0_402:
	v_lshl_add_u64 v[2:3], s[54:55], 0, v[144:145]
	v_add_co_u32_e32 v4, vcc, s90, v2
	v_lshl_add_u64 v[10:11], s[54:55], 0, v[142:143]
	s_nop 0
	v_addc_co_u32_e32 v5, vcc, 0, v3, vcc
	v_add_co_u32_e32 v6, vcc, s91, v2
	s_waitcnt lgkmcnt(0)
	s_nop 0
	v_addc_co_u32_e32 v7, vcc, 0, v3, vcc
	v_add_co_u32_e32 v12, vcc, 0x20000000, v10
	s_barrier
	s_nop 0
	v_addc_co_u32_e32 v13, vcc, 0, v11, vcc
	v_add_co_u32_e32 v14, vcc, 0x20800000, v10
	global_load_dwordx4 v[2:5], v[4:5], off offset:2048
	s_nop 0
	global_load_dwordx4 v[6:9], v[6:7], off offset:2048
	v_addc_co_u32_e32 v15, vcc, 0, v11, vcc
	global_load_dwordx4 v[10:13], v[12:13], off offset:128
	s_nop 0
	global_load_dwordx4 v[128:131], v[14:15], off offset:128
	s_and_b32 s9, s19, 1
	s_add_i32 s8, s0, 64
	s_cmp_gt_u32 s8, s21
	s_cbranch_scc1 .LBB0_408
	s_mul_i32 s1, s9, 0x8800
	s_add_i32 s12, s1, 0
	s_add_i32 s1, s20, s12
	v_add3_u32 v0, s1, v197, v140
	ds_read_b128 v[80:83], v0
	ds_read_b128 v[148:151], v0 offset:32
	ds_read_b128 v[84:87], v0 offset:8704
	ds_read_b128 v[152:155], v0 offset:8736
	ds_read_b128 v[156:159], v0 offset:64
	ds_read_b128 v[160:163], v0 offset:96
	ds_read_b128 v[164:167], v0 offset:8768
	ds_read_b128 v[168:171], v0 offset:8800
	ds_read2_b32 v[14:15], v202 offset0:59 offset1:58
	ds_read2_b32 v[218:219], v202 offset0:27 offset1:26
	ds_read2_b32 v[220:221], v202 offset0:57 offset1:56
	ds_read2_b32 v[222:223], v202 offset0:25 offset1:24
	ds_read2_b32 v[224:225], v202 offset0:51 offset1:50
	ds_read2_b32 v[174:175], v202 offset0:19 offset1:18
	ds_read2_b32 v[226:227], v202 offset0:49 offset1:48
	s_waitcnt lgkmcnt(14)
	s_waitcnt vmcnt(7)
	v_mfma_f32_32x32x16_bf16 v[96:111], v[80:83], v[124:127], 0
	s_add_i32 s13, s0, 0x7f
	s_mov_b64 s[0:1], -1
	s_cmp_gt_u32 s13, s15
	ds_read2_b32 v[172:173], v202 offset0:17 offset1:16
	s_waitcnt lgkmcnt(13)
	v_mfma_f32_32x32x16_bf16 v[80:95], v[84:87], v[124:127], 0
	s_waitcnt vmcnt(6)
	v_mfma_f32_32x32x16_bf16 v[96:111], v[148:151], v[120:123], v[96:111]
	ds_read2_b32 v[242:243], v202 offset0:43 offset1:42
	ds_read2_b32 v[182:183], v202 offset0:11 offset1:10
	s_waitcnt lgkmcnt(14)
	v_mfma_f32_32x32x16_bf16 v[80:95], v[152:155], v[120:123], v[80:95]
	ds_read2_b32 v[176:177], v202 offset0:41 offset1:40
	s_waitcnt lgkmcnt(14)
	s_waitcnt vmcnt(5)
	v_mfma_f32_32x32x16_bf16 v[96:111], v[156:159], v[116:119], v[96:111]
	ds_read2_b32 v[184:185], v202 offset0:9 offset1:8
	s_waitcnt lgkmcnt(13)
	v_mfma_f32_32x32x16_bf16 v[80:95], v[164:167], v[116:119], v[80:95]
	s_waitcnt vmcnt(4)
	v_mfma_f32_32x32x16_bf16 v[96:111], v[160:163], v[112:115], v[96:111]
	ds_read2_b32 v[180:181], v202 offset0:35 offset1:34
	ds_read2_b32 v[188:189], v202 offset0:3 offset1:2
	s_waitcnt lgkmcnt(14)
	v_mfma_f32_32x32x16_bf16 v[80:95], v[168:171], v[112:115], v[80:95]
	ds_read2_b32 v[178:179], v202 offset0:33 offset1:32
	s_nop 11
	s_cbranch_scc1 .LdaB_bias_masked
	s_waitcnt lgkmcnt(14)
	v_add_f32_e32 v14, v96, v14
	v_add_f32_e32 v15, v97, v15
	ds_read2_b32 v[186:187], v202 offset0:1 offset1:0
	s_waitcnt lgkmcnt(14)
	v_add_f32_e32 v166, v80, v218
	v_add_f32_e32 v167, v81, v219
	s_waitcnt lgkmcnt(13)
	v_add_f32_e32 v148, v98, v220
	v_add_f32_e32 v149, v99, v221
	s_waitcnt lgkmcnt(12)
	v_add_f32_e32 v168, v82, v222
	v_add_f32_e32 v169, v83, v223
	s_waitcnt lgkmcnt(11)
	v_add_f32_e32 v152, v100, v224
	v_add_f32_e32 v153, v101, v225
	s_waitcnt lgkmcnt(10)
	v_add_f32_e32 v174, v84, v174
	v_add_f32_e32 v175, v85, v175
	s_waitcnt lgkmcnt(9)
	v_add_f32_e32 v150, v102, v226
	v_add_f32_e32 v151, v103, v227
	s_waitcnt lgkmcnt(8)
	v_add_f32_e32 v172, v86, v172
	v_add_f32_e32 v173, v87, v173
	s_waitcnt lgkmcnt(7)
	v_add_f32_e32 v170, v104, v242
	v_add_f32_e32 v171, v105, v243
	s_waitcnt lgkmcnt(6)
	v_add_f32_e32 v182, v88, v182
	v_add_f32_e32 v183, v89, v183
	s_waitcnt lgkmcnt(5)
	v_add_f32_e32 v176, v106, v176
	v_add_f32_e32 v177, v107, v177
	s_waitcnt lgkmcnt(4)
	v_add_f32_e32 v184, v90, v184
	v_add_f32_e32 v185, v91, v185
	s_waitcnt lgkmcnt(3)
	v_add_f32_e32 v180, v108, v180
	v_add_f32_e32 v181, v109, v181
	s_waitcnt lgkmcnt(2)
	v_add_f32_e32 v188, v92, v188
	v_add_f32_e32 v189, v93, v189
	s_waitcnt lgkmcnt(1)
	v_add_f32_e32 v178, v110, v178
	v_add_f32_e32 v179, v111, v179
	s_waitcnt lgkmcnt(0)
	v_add_f32_e32 v186, v94, v186
	v_add_f32_e32 v187, v95, v187
	v_max_f32_e32 v80, v14, v166
	v_max_f32_e32 v81, v15, v167
	v_max3_f32 v82, v80, s84, v81
	v_max_f32_e32 v80, v148, v168
	v_max_f32_e32 v81, v149, v169
	v_max3_f32 v82, v82, v80, v81
	v_max_f32_e32 v80, v152, v174
	v_max_f32_e32 v81, v153, v175
	v_max3_f32 v82, v82, v80, v81
	v_max_f32_e32 v80, v150, v172
	v_max_f32_e32 v81, v151, v173
	v_max3_f32 v82, v82, v80, v81
	v_max_f32_e32 v80, v170, v182
	v_max_f32_e32 v81, v171, v183
	v_max3_f32 v82, v82, v80, v81
	v_max_f32_e32 v80, v176, v184
	v_max_f32_e32 v81, v177, v185
	v_max3_f32 v82, v82, v80, v81
	v_max_f32_e32 v80, v180, v188
	v_max_f32_e32 v81, v181, v189
	v_max3_f32 v82, v82, v80, v81
	v_max_f32_e32 v80, v178, v186
	v_max_f32_e32 v81, v179, v187
	v_max3_f32 v0, v82, v80, v81
	s_branch .LBB0_407
; #define LAS __attribute__((address_space(3)))
; __device__ __forceinline__ float max_x32(float v) { auto rr = __builtin_amdgcn_permlane32_swap(__float_as_uint(v), __float_as_uint(v), false, false); return fmaxf(__uint_as_float(rr[0]), __uint_as_float(rr[1])); }
; template <int MODE> ...
;     ...
;                 const volatile LAS float* bl = (const volatile LAS float*)(biasL + mp * 2048);
;                 float bb0[16], bb1[16];
; #pragma unroll
;                 for (int r = 0; r < 16; ++r) {
;                     const int rel0 = relbase - ((r & 3) + 8 * (r >> 2));
;                     bb0[r] = bl[min(max(rel0, 0), cmax)]; bb1[r] = bl[min(max(rel0 - 32, 0), cmax)];
;                 }
; #pragma unroll
;                 for (int r = 0; r < 16; ++r) {
;                     const int rel0 = relbase - ((r & 3) + 8 * (r >> 2)), rel1 = rel0 - 32;
;                     bool ok0 = rel0 >= 0, ok1 = rel1 >= 0;
;                     if (MODE == 1) { ok0 = ok0 && (rel0 <= 128); ok1 = ok1 && (rel1 <= 128); }
;                     const float t0 = s0[r] + bb0[r], t1 = s1[r] + bb1[r];
;                     s0[r] = ok0 ? t0 : -1e30f; s1[r] = ok1 ? t1 : -1e30f;
;                     mx = fmaxf(mx, fmaxf(s0[r], s1[r]));
;                 }
;             }
;             mx = max_x32(mx);
.LdaB_bias_masked:
	v_add_u32_e32 v0, s89, v201
	s_waitcnt lgkmcnt(14)
	v_add_f32_e32 v14, v96, v14
	v_add_f32_e32 v15, v97, v15
	ds_read2_b32 v[186:187], v202 offset0:1 offset1:0
	v_cmp_lt_i32_e32 vcc, -1, v0
	v_cmp_lt_i32_e64 s[100:101], 0, v0
	s_nop 1
	v_cndmask_b32_e32 v14, v214, v14, vcc
	v_cndmask_b32_e64 v15, v214, v15, s[100:101]
	s_waitcnt lgkmcnt(14)
	v_add_f32_e32 v166, v80, v218
	v_add_f32_e32 v167, v81, v219
	v_cmp_lt_i32_e32 vcc, 31, v0
	v_cmp_lt_i32_e64 s[100:101], 32, v0
	s_nop 1
	v_cndmask_b32_e32 v166, v214, v166, vcc
	v_cndmask_b32_e64 v167, v214, v167, s[100:101]
	s_waitcnt lgkmcnt(13)
	v_add_f32_e32 v148, v98, v220
	v_add_f32_e32 v149, v99, v221
	v_cmp_lt_i32_e32 vcc, 1, v0
	v_cmp_lt_i32_e64 s[100:101], 2, v0
	s_nop 1
	v_cndmask_b32_e32 v148, v214, v148, vcc
	v_cndmask_b32_e64 v149, v214, v149, s[100:101]
	s_waitcnt lgkmcnt(12)
	v_add_f32_e32 v168, v82, v222
	v_add_f32_e32 v169, v83, v223
	v_cmp_lt_i32_e32 vcc, 33, v0
	v_cmp_lt_i32_e64 s[100:101], 34, v0
	s_nop 1
	v_cndmask_b32_e32 v168, v214, v168, vcc
	v_cndmask_b32_e64 v169, v214, v169, s[100:101]
	s_waitcnt lgkmcnt(11)
	v_add_f32_e32 v152, v100, v224
	v_add_f32_e32 v153, v101, v225
	v_cmp_lt_i32_e32 vcc, 7, v0
	v_cmp_lt_i32_e64 s[100:101], 8, v0
	s_nop 1
	v_cndmask_b32_e32 v152, v214, v152, vcc
	v_cndmask_b32_e64 v153, v214, v153, s[100:101]
	s_waitcnt lgkmcnt(10)
	v_add_f32_e32 v174, v84, v174
	v_add_f32_e32 v175, v85, v175
	v_cmp_lt_i32_e32 vcc, 39, v0
	v_cmp_lt_i32_e64 s[100:101], 40, v0
	s_nop 1
	v_cndmask_b32_e32 v174, v214, v174, vcc
	v_cndmask_b32_e64 v175, v214, v175, s[100:101]
	s_waitcnt lgkmcnt(9)
	v_add_f32_e32 v150, v102, v226
	v_add_f32_e32 v151, v103, v227
	v_cmp_lt_i32_e32 vcc, 9, v0
	v_cmp_lt_i32_e64 s[100:101], 10, v0
	s_nop 1
	v_cndmask_b32_e32 v150, v214, v150, vcc
	v_cndmask_b32_e64 v151, v214, v151, s[100:101]
	s_waitcnt lgkmcnt(8)
	v_add_f32_e32 v172, v86, v172
	v_add_f32_e32 v173, v87, v173
	v_cmp_lt_i32_e32 vcc, 41, v0
	v_cmp_lt_i32_e64 s[100:101], 42, v0
	s_nop 1
	v_cndmask_b32_e32 v172, v214, v172, vcc
	v_cndmask_b32_e64 v173, v214, v173, s[100:101]
	s_waitcnt lgkmcnt(7)
	v_add_f32_e32 v170, v104, v242
	v_add_f32_e32 v171, v105, v243
	v_cmp_lt_i32_e32 vcc, 15, v0
	v_cmp_lt_i32_e64 s[100:101], 16, v0
	s_nop 1
	v_cndmask_b32_e32 v170, v214, v170, vcc
	v_cndmask_b32_e64 v171, v214, v171, s[100:101]
	s_waitcnt lgkmcnt(6)
	v_add_f32_e32 v182, v88, v182
	v_add_f32_e32 v183, v89, v183
	v_cmp_lt_i32_e32 vcc, 47, v0
	v_cmp_lt_i32_e64 s[100:101], 48, v0
	s_nop 1
	v_cndmask_b32_e32 v182, v214, v182, vcc
	v_cndmask_b32_e64 v183, v214, v183, s[100:101]
	s_waitcnt lgkmcnt(5)
	v_add_f32_e32 v176, v106, v176
	v_add_f32_e32 v177, v107, v177
	v_cmp_lt_i32_e32 vcc, 17, v0
	v_cmp_lt_i32_e64 s[100:101], 18, v0
	s_nop 1
	v_cndmask_b32_e32 v176, v214, v176, vcc
	v_cndmask_b32_e64 v177, v214, v177, s[100:101]
	s_waitcnt lgkmcnt(4)
	v_add_f32_e32 v184, v90, v184
	v_add_f32_e32 v185, v91, v185
	v_cmp_lt_i32_e32 vcc, 49, v0
	v_cmp_lt_i32_e64 s[100:101], 50, v0
	s_nop 1
	v_cndmask_b32_e32 v184, v214, v184, vcc
	v_cndmask_b32_e64 v185, v214, v185, s[100:101]
	s_waitcnt lgkmcnt(3)
	v_add_f32_e32 v180, v108, v180
	v_add_f32_e32 v181, v109, v181
	v_cmp_lt_i32_e32 vcc, 23, v0
	v_cmp_lt_i32_e64 s[100:101], 24, v0
	s_nop 1
	v_cndmask_b32_e32 v180, v214, v180, vcc
	v_cndmask_b32_e64 v181, v214, v181, s[100:101]
	s_waitcnt lgkmcnt(2)
	v_add_f32_e32 v188, v92, v188
	v_add_f32_e32 v189, v93, v189
	v_cmp_lt_i32_e32 vcc, 55, v0
	v_cmp_lt_i32_e64 s[100:101], 56, v0
	s_nop 1
	v_cndmask_b32_e32 v188, v214, v188, vcc
	v_cndmask_b32_e64 v189, v214, v189, s[100:101]
	s_waitcnt lgkmcnt(1)
	v_add_f32_e32 v178, v110, v178
	v_add_f32_e32 v179, v111, v179
	v_cmp_lt_i32_e32 vcc, 25, v0
	v_cmp_lt_i32_e64 s[100:101], 26, v0
	s_nop 1
	v_cndmask_b32_e32 v178, v214, v178, vcc
	v_cndmask_b32_e64 v179, v214, v179, s[100:101]
	s_waitcnt lgkmcnt(0)
	v_add_f32_e32 v186, v94, v186
	v_add_f32_e32 v187, v95, v187
	v_cmp_lt_i32_e32 vcc, 57, v0
	v_cmp_lt_i32_e64 s[100:101], 58, v0
	s_nop 1
	v_cndmask_b32_e32 v186, v214, v186, vcc
	v_cndmask_b32_e64 v187, v214, v187, s[100:101]
	v_max_f32_e32 v80, v14, v166
	v_max_f32_e32 v81, v15, v167
	v_max3_f32 v82, v80, s84, v81
	v_max_f32_e32 v80, v148, v168
	v_max_f32_e32 v81, v149, v169
	v_max3_f32 v82, v82, v80, v81
	v_max_f32_e32 v80, v152, v174
	v_max_f32_e32 v81, v153, v175
	v_max3_f32 v82, v82, v80, v81
	v_max_f32_e32 v80, v150, v172
	v_max_f32_e32 v81, v151, v173
	v_max3_f32 v82, v82, v80, v81
	v_max_f32_e32 v80, v170, v182
	v_max_f32_e32 v81, v171, v183
	v_max3_f32 v82, v82, v80, v81
	v_max_f32_e32 v80, v176, v184
	v_max_f32_e32 v81, v177, v185
	v_max3_f32 v82, v82, v80, v81
	v_max_f32_e32 v80, v180, v188
	v_max_f32_e32 v81, v181, v189
	v_max3_f32 v82, v82, v80, v81
	v_max_f32_e32 v80, v178, v186
	v_max_f32_e32 v81, v179, v187
	v_max3_f32 v0, v82, v80, v81

; template <int MODE> ...
;     ...
;             const LAS unsigned char* kb = lds + bufsel * AT_BUF; const LAS unsigned char* vb = kb + AT_KBYTES;
;             f32x16 s0, s1;
; #pragma unroll
;             for (int r = 0; r < 16; ++r) { s0[r] = 0.f; s1[r] = 0.f; }
;             {
;                 bf16x8 ka[4], kc[4];
; #pragma unroll
;                 for (int ds = 0; ds < 4; ++ds) {
;                     ka[ds] = *(const LAS bf16x8*)(kb + r32 * AT_KROW + mp * 128 + (16 * ds + 8 * hi) * 2);
;                     kc[ds] = *(const LAS bf16x8*)(kb + (32 + r32) * AT_KROW + mp * 128 + (16 * ds + 8 * hi) * 2);
;                 }
;                 __builtin_amdgcn_sched_barrier(0);
; #pragma unroll
;                 for (int ds = 0; ds < 4; ++ds) {
;                     s0 = __builtin_amdgcn_mfma_f32_32x32x16_bf16(ka[ds], qf[ds], s0, 0, 0, 0);
;                     s1 = __builtin_amdgcn_mfma_f32_32x32x16_bf16(kc[ds], qf[ds], s1, 0, 0, 0);
;                 }
;             }
;             const int relbase = qi - kv0 - 4 * hi;
;             constexpr int cmax = (MODE == 0) ? 2047 : 128;
;             float mx = -1e30f;
;             bool interior = (kv0 + 63 <= q_lo);
;             if (MODE == 1) interior = interior && (q_lo + 31 - kv0 <= 128);
;             if (interior) {
;                 const LAS float* p = biasL + mp * 2048 + (relbase - 59);
; #pragma unroll
;                 for (int r = 0; r < 16; ++r) {
;                     const int o = 59 - ((r & 3) + 8 * (r >> 2));
;                     s0[r] += p[o]; s1[r] += p[o - 32];
;                     mx = fmaxf(mx, fmaxf(s0[r], s1[r]));
;                 }
;             } else {
;                 const volatile LAS float* bl = (const volatile LAS float*)(biasL + mp * 2048);
;                 float bb0[16], bb1[16];
; #pragma unroll
;                 for (int r = 0; r < 16; ++r) {
;                     const int rel0 = relbase - ((r & 3) + 8 * (r >> 2));
;                     bb0[r] = bl[min(max(rel0, 0), cmax)]; bb1[r] = bl[min(max(rel0 - 32, 0), cmax)];
;                 }
; #pragma unroll
;                 for (int r = 0; r < 16; ++r) {
;                     const int rel0 = relbase - ((r & 3) + 8 * (r >> 2)), rel1 = rel0 - 32;
;                     bool ok0 = rel0 >= 0, ok1 = rel1 >= 0;
;                     if (MODE == 1) { ok0 = ok0 && (rel0 <= 128); ok1 = ok1 && (rel1 <= 128); }
.LBB0_439:
	s_mul_i32 s19, s15, 0x8800
	s_add_i32 s42, s19, 0
	s_add_i32 s19, s34, s42
	v_add3_u32 v42, s19, v179, v120
	ds_read_b128 v[34:37], v42
	ds_read_b128 v[132:135], v42 offset:32
	ds_read_b128 v[38:41], v42 offset:8704
	ds_read_b128 v[136:139], v42 offset:8736
	ds_read_b128 v[140:143], v42 offset:64
	ds_read_b128 v[148:151], v42 offset:96
	ds_read_b128 v[152:155], v42 offset:8768
	ds_read_b128 v[156:159], v42 offset:8800
	s_waitcnt lgkmcnt(0)
	v_mfma_f32_32x32x16_bf16 v[50:65], v[34:37], v[66:69], 0
	s_cmp_le_i32 s18, s28
	s_cselect_b64 s[18:19], -1, 0
	s_cmpk_lt_i32 s39, 0x81
	s_cselect_b64 s[48:49], -1, 0
	s_and_b64 s[48:49], s[18:19], s[48:49]
	s_mov_b64 s[18:19], -1
	s_andn2_b64 vcc, exec, s[48:49]
	v_mfma_f32_32x32x16_bf16 v[34:49], v[38:41], v[66:69], 0
	v_mfma_f32_32x32x16_bf16 v[50:65], v[132:135], v[70:73], v[50:65]
	v_mfma_f32_32x32x16_bf16 v[34:49], v[136:139], v[70:73], v[34:49]
	v_mfma_f32_32x32x16_bf16 v[50:65], v[140:143], v[74:77], v[50:65]
	v_mfma_f32_32x32x16_bf16 v[34:49], v[152:155], v[74:77], v[34:49]
	v_mfma_f32_32x32x16_bf16 v[50:65], v[148:151], v[78:81], v[50:65]
	v_mfma_f32_32x32x16_bf16 v[34:49], v[156:159], v[78:81], v[34:49]
	s_cbranch_vccz .Ldil_bias_interior
	v_add_u32_e32 v185, s39, v182
	ds_read2_b32 v[132:133], v183 offset0:59 offset1:58
	ds_read2_b32 v[136:137], v183 offset0:27 offset1:26
	ds_read2_b32 v[134:135], v183 offset0:57 offset1:56
	ds_read2_b32 v[138:139], v183 offset0:25 offset1:24
	ds_read2_b32 v[140:141], v183 offset0:51 offset1:50
	ds_read2_b32 v[142:143], v183 offset0:19 offset1:18
	ds_read2_b32 v[144:145], v183 offset0:49 offset1:48
	ds_read2_b32 v[150:151], v183 offset0:17 offset1:16
	ds_read2_b32 v[148:149], v183 offset0:43 offset1:42
	ds_read2_b32 v[152:153], v183 offset0:11 offset1:10
	ds_read2_b32 v[166:167], v183 offset0:41 offset1:40
	ds_read2_b32 v[168:169], v183 offset0:9 offset1:8
	s_waitcnt lgkmcnt(11)
	v_add_f32_e32 v132, v50, v132
	v_add_f32_e32 v133, v51, v133
	v_add_u32_e32 v186, 0xffffffe1, v185
	v_add_u32_e32 v187, 0xffffffe0, v185
	v_cmp_gt_u32_e32 vcc, s85, v186
	v_cmp_gt_u32_e64 s[100:101], s85, v187
	s_nop 1
	v_cndmask_b32_e32 v132, v214, v132, vcc
	v_cndmask_b32_e64 v133, v214, v133, s[100:101]
	s_waitcnt lgkmcnt(10)
	v_add_f32_e32 v136, v34, v136
	v_add_f32_e32 v137, v35, v137
	v_add_u32_e32 v186, 0xffffffc1, v185
	v_add_u32_e32 v187, 0xffffffc0, v185
	v_cmp_gt_u32_e32 vcc, s85, v186
	v_cmp_gt_u32_e64 s[100:101], s85, v187
	s_nop 1
	v_cndmask_b32_e32 v136, v214, v136, vcc
	v_cndmask_b32_e64 v137, v214, v137, s[100:101]
	s_waitcnt lgkmcnt(9)
	v_add_f32_e32 v134, v52, v134
	v_add_f32_e32 v135, v53, v135
	v_add_u32_e32 v186, 0xffffffdf, v185
	v_add_u32_e32 v187, 0xffffffde, v185
	v_cmp_gt_u32_e32 vcc, s85, v186
	v_cmp_gt_u32_e64 s[100:101], s85, v187
	s_nop 1
	v_cndmask_b32_e32 v134, v214, v134, vcc
	v_cndmask_b32_e64 v135, v214, v135, s[100:101]
	s_waitcnt lgkmcnt(8)
	v_add_f32_e32 v138, v36, v138
	v_add_f32_e32 v139, v37, v139
	v_add_u32_e32 v186, 0xffffffbf, v185
	v_add_u32_e32 v187, 0xffffffbe, v185
	v_cmp_gt_u32_e32 vcc, s85, v186
	v_cmp_gt_u32_e64 s[100:101], s85, v187
	s_nop 1
	v_cndmask_b32_e32 v138, v214, v138, vcc
	v_cndmask_b32_e64 v139, v214, v139, s[100:101]
	ds_read2_b32 v[170:171], v183 offset0:35 offset1:34
	ds_read2_b32 v[172:173], v183 offset0:3 offset1:2
	ds_read2_b32 v[174:175], v183 offset0:33 offset1:32
	ds_read2_b32 v[176:177], v183 offset0:1 offset1:0
	s_waitcnt lgkmcnt(11)
	v_add_f32_e32 v140, v54, v140
	v_add_f32_e32 v141, v55, v141
	v_add_u32_e32 v186, 0xffffffd9, v185
	v_add_u32_e32 v187, 0xffffffd8, v185
	v_cmp_gt_u32_e32 vcc, s85, v186
	v_cmp_gt_u32_e64 s[100:101], s85, v187
	s_nop 1
	v_cndmask_b32_e32 v140, v214, v140, vcc
	v_cndmask_b32_e64 v141, v214, v141, s[100:101]
	s_waitcnt lgkmcnt(10)
	v_add_f32_e32 v142, v38, v142
	v_add_f32_e32 v143, v39, v143
	v_add_u32_e32 v186, 0xffffffb9, v185
	v_add_u32_e32 v187, 0xffffffb8, v185
	v_cmp_gt_u32_e32 vcc, s85, v186
	v_cmp_gt_u32_e64 s[100:101], s85, v187
	s_nop 1
	v_cndmask_b32_e32 v142, v214, v142, vcc
	v_cndmask_b32_e64 v143, v214, v143, s[100:101]
	s_waitcnt lgkmcnt(9)
	v_add_f32_e32 v144, v56, v144
	v_add_f32_e32 v145, v57, v145
	v_add_u32_e32 v186, 0xffffffd7, v185
	v_add_u32_e32 v187, 0xffffffd6, v185
	v_cmp_gt_u32_e32 vcc, s85, v186
	v_cmp_gt_u32_e64 s[100:101], s85, v187
	s_nop 1
	v_cndmask_b32_e32 v144, v214, v144, vcc
	v_cndmask_b32_e64 v145, v214, v145, s[100:101]
	s_waitcnt lgkmcnt(8)
	v_add_f32_e32 v150, v40, v150
	v_add_f32_e32 v151, v41, v151
	v_add_u32_e32 v186, 0xffffffb7, v185
	v_add_u32_e32 v187, 0xffffffb6, v185
	v_cmp_gt_u32_e32 vcc, s85, v186
	v_cmp_gt_u32_e64 s[100:101], s85, v187
	s_nop 1
	v_cndmask_b32_e32 v150, v214, v150, vcc
	v_cndmask_b32_e64 v151, v214, v151, s[100:101]
	s_waitcnt lgkmcnt(7)
	v_add_f32_e32 v148, v58, v148
	v_add_f32_e32 v149, v59, v149
	v_add_u32_e32 v186, 0xffffffd1, v185
	v_add_u32_e32 v187, 0xffffffd0, v185
	v_cmp_gt_u32_e32 vcc, s85, v186
	v_cmp_gt_u32_e64 s[100:101], s85, v187
	s_nop 1
	v_cndmask_b32_e32 v148, v214, v148, vcc
	v_cndmask_b32_e64 v149, v214, v149, s[100:101]
	s_waitcnt lgkmcnt(6)
	v_add_f32_e32 v152, v42, v152
	v_add_f32_e32 v153, v43, v153
	v_add_u32_e32 v186, 0xffffffb1, v185
	v_add_u32_e32 v187, 0xffffffb0, v185
	v_cmp_gt_u32_e32 vcc, s85, v186
	v_cmp_gt_u32_e64 s[100:101], s85, v187
	s_nop 1
	v_cndmask_b32_e32 v152, v214, v152, vcc
	v_cndmask_b32_e64 v153, v214, v153, s[100:101]
	s_waitcnt lgkmcnt(5)
; #define LAS __attribute__((address_space(3)))
; __device__ __forceinline__ float max_x32(float v) { auto rr = __builtin_amdgcn_permlane32_swap(__float_as_uint(v), __float_as_uint(v), false, false); return fmaxf(__uint_as_float(rr[0]), __uint_as_float(rr[1])); }
; template <int MODE> ...
;     ...
;             const int relbase = qi - kv0 - 4 * hi;
;             constexpr int cmax = (MODE == 0) ? 2047 : 128;
;             float mx = -1e30f;
;             bool interior = (kv0 + 63 <= q_lo);
;             if (MODE == 1) interior = interior && (q_lo + 31 - kv0 <= 128);
;             if (interior) {
;                 const LAS float* p = biasL + mp * 2048 + (relbase - 59);
; #pragma unroll
;                 for (int r = 0; r < 16; ++r) {
;                     const int o = 59 - ((r & 3) + 8 * (r >> 2));
;                     s0[r] += p[o]; s1[r] += p[o - 32];
;                     mx = fmaxf(mx, fmaxf(s0[r], s1[r]));
;                 }
;             } else {
;                 const volatile LAS float* bl = (const volatile LAS float*)(biasL + mp * 2048);
;                 float bb0[16], bb1[16];
; #pragma unroll
;                 for (int r = 0; r < 16; ++r) {
;                     const int rel0 = relbase - ((r & 3) + 8 * (r >> 2));
;                     bb0[r] = bl[min(max(rel0, 0), cmax)]; bb1[r] = bl[min(max(rel0 - 32, 0), cmax)];
;                 }
; #pragma unroll
;                 for (int r = 0; r < 16; ++r) {
;                     const int rel0 = relbase - ((r & 3) + 8 * (r >> 2)), rel1 = rel0 - 32;
;                     bool ok0 = rel0 >= 0, ok1 = rel1 >= 0;
;                     if (MODE == 1) { ok0 = ok0 && (rel0 <= 128); ok1 = ok1 && (rel1 <= 128); }
;                     const float t0 = s0[r] + bb0[r], t1 = s1[r] + bb1[r];
;                     s0[r] = ok0 ? t0 : -1e30f; s1[r] = ok1 ? t1 : -1e30f;
;                     mx = fmaxf(mx, fmaxf(s0[r], s1[r]));
;                 }
;             }
;             mx = max_x32(mx);
	v_add_f32_e32 v166, v60, v166
	v_add_f32_e32 v167, v61, v167
	v_add_u32_e32 v186, 0xffffffcf, v185
	v_add_u32_e32 v187, 0xffffffce, v185
	v_cmp_gt_u32_e32 vcc, s85, v186
	v_cmp_gt_u32_e64 s[100:101], s85, v187
	s_nop 1
	v_cndmask_b32_e32 v166, v214, v166, vcc
	v_cndmask_b32_e64 v167, v214, v167, s[100:101]
	s_waitcnt lgkmcnt(4)
	v_add_f32_e32 v168, v44, v168
	v_add_f32_e32 v169, v45, v169
	v_add_u32_e32 v186, 0xffffffaf, v185
	v_add_u32_e32 v187, 0xffffffae, v185
	v_cmp_gt_u32_e32 vcc, s85, v186
	v_cmp_gt_u32_e64 s[100:101], s85, v187
	s_nop 1
	v_cndmask_b32_e32 v168, v214, v168, vcc
	v_cndmask_b32_e64 v169, v214, v169, s[100:101]
	s_waitcnt lgkmcnt(3)
	v_add_f32_e32 v170, v62, v170
	v_add_f32_e32 v171, v63, v171
	v_add_u32_e32 v186, 0xffffffc9, v185
	v_add_u32_e32 v187, 0xffffffc8, v185
	v_cmp_gt_u32_e32 vcc, s85, v186
	v_cmp_gt_u32_e64 s[100:101], s85, v187
	s_nop 1
	v_cndmask_b32_e32 v170, v214, v170, vcc
	v_cndmask_b32_e64 v171, v214, v171, s[100:101]
	s_waitcnt lgkmcnt(2)
	v_add_f32_e32 v172, v46, v172
	v_add_f32_e32 v173, v47, v173
	v_add_u32_e32 v186, 0xffffffa9, v185
	v_add_u32_e32 v187, 0xffffffa8, v185
	v_cmp_gt_u32_e32 vcc, s85, v186
	v_cmp_gt_u32_e64 s[100:101], s85, v187
	s_nop 1
	v_cndmask_b32_e32 v172, v214, v172, vcc
	v_cndmask_b32_e64 v173, v214, v173, s[100:101]
	s_waitcnt lgkmcnt(1)
	v_add_f32_e32 v174, v64, v174
	v_add_f32_e32 v175, v65, v175
	v_add_u32_e32 v186, 0xffffffc7, v185
	v_add_u32_e32 v187, 0xffffffc6, v185
	v_cmp_gt_u32_e32 vcc, s85, v186
	v_cmp_gt_u32_e64 s[100:101], s85, v187
	s_nop 1
	v_cndmask_b32_e32 v174, v214, v174, vcc
	v_cndmask_b32_e64 v175, v214, v175, s[100:101]
	s_waitcnt lgkmcnt(0)
	v_add_f32_e32 v176, v48, v176
	v_add_f32_e32 v177, v49, v177
	v_add_u32_e32 v186, 0xffffffa7, v185
	v_add_u32_e32 v187, 0xffffffa6, v185
	v_cmp_gt_u32_e32 vcc, s85, v186
	v_cmp_gt_u32_e64 s[100:101], s85, v187
	s_nop 1
	v_cndmask_b32_e32 v176, v214, v176, vcc
	v_cndmask_b32_e64 v177, v214, v177, s[100:101]
	v_max_f32_e32 v34, v132, v136
	v_max_f32_e32 v35, v133, v137
	v_max3_f32 v36, v34, s84, v35
	v_max_f32_e32 v34, v134, v138
	v_max_f32_e32 v35, v135, v139
	v_max3_f32 v36, v36, v34, v35
	v_max_f32_e32 v34, v140, v142
	v_max_f32_e32 v35, v141, v143
	v_max3_f32 v36, v36, v34, v35
	v_max_f32_e32 v34, v144, v150
	v_max_f32_e32 v35, v145, v151
	v_max3_f32 v36, v36, v34, v35
	v_max_f32_e32 v34, v148, v152
	v_max_f32_e32 v35, v149, v153
	v_max3_f32 v36, v36, v34, v35
	v_max_f32_e32 v34, v166, v168
	v_max_f32_e32 v35, v167, v169
	v_max3_f32 v36, v36, v34, v35
	v_max_f32_e32 v34, v170, v172
	v_max_f32_e32 v35, v171, v173
	v_max3_f32 v36, v36, v34, v35
	v_max_f32_e32 v34, v174, v176
	v_max_f32_e32 v35, v175, v177
	v_max3_f32 v184, v36, v34, v35
	s_branch .LBB0_443
.Ldil_bias_interior:
	ds_read2_b32 v[132:133], v183 offset0:59 offset1:58
	ds_read2_b32 v[136:137], v183 offset0:27 offset1:26
	ds_read2_b32 v[134:135], v183 offset0:57 offset1:56
	ds_read2_b32 v[138:139], v183 offset0:25 offset1:24
	ds_read2_b32 v[140:141], v183 offset0:51 offset1:50
	ds_read2_b32 v[142:143], v183 offset0:19 offset1:18
	ds_read2_b32 v[144:145], v183 offset0:49 offset1:48
	ds_read2_b32 v[150:151], v183 offset0:17 offset1:16
	ds_read2_b32 v[148:149], v183 offset0:43 offset1:42
	ds_read2_b32 v[152:153], v183 offset0:11 offset1:10
	ds_read2_b32 v[166:167], v183 offset0:41 offset1:40
	ds_read2_b32 v[168:169], v183 offset0:9 offset1:8
	s_waitcnt lgkmcnt(11)
	v_add_f32_e32 v132, v50, v132
	v_add_f32_e32 v133, v51, v133
	s_waitcnt lgkmcnt(10)
	v_add_f32_e32 v136, v34, v136
	v_add_f32_e32 v137, v35, v137
	s_waitcnt lgkmcnt(9)
	v_add_f32_e32 v134, v52, v134
	v_add_f32_e32 v135, v53, v135
	s_waitcnt lgkmcnt(8)
	v_add_f32_e32 v138, v36, v138
	v_add_f32_e32 v139, v37, v139
	ds_read2_b32 v[170:171], v183 offset0:35 offset1:34
	ds_read2_b32 v[172:173], v183 offset0:3 offset1:2
	ds_read2_b32 v[174:175], v183 offset0:33 offset1:32
	ds_read2_b32 v[176:177], v183 offset0:1 offset1:0
	s_waitcnt lgkmcnt(11)
	v_add_f32_e32 v140, v54, v140
	v_add_f32_e32 v141, v55, v141
	s_waitcnt lgkmcnt(10)
	v_add_f32_e32 v142, v38, v142
	v_add_f32_e32 v143, v39, v143
	s_waitcnt lgkmcnt(9)
	v_add_f32_e32 v144, v56, v144
	v_add_f32_e32 v145, v57, v145
	s_waitcnt lgkmcnt(8)
	v_add_f32_e32 v150, v40, v150
	v_add_f32_e32 v151, v41, v151
	s_waitcnt lgkmcnt(7)
	v_add_f32_e32 v148, v58, v148
	v_add_f32_e32 v149, v59, v149
	s_waitcnt lgkmcnt(6)
	v_add_f32_e32 v152, v42, v152
	v_add_f32_e32 v153, v43, v153
	s_waitcnt lgkmcnt(5)
	v_add_f32_e32 v166, v60, v166
	v_add_f32_e32 v167, v61, v167
	s_waitcnt lgkmcnt(4)
	v_add_f32_e32 v168, v44, v168
	v_add_f32_e32 v169, v45, v169
	s_waitcnt lgkmcnt(3)
	v_add_f32_e32 v170, v62, v170
	v_add_f32_e32 v171, v63, v171
	s_waitcnt lgkmcnt(2)
	v_add_f32_e32 v172, v46, v172
	v_add_f32_e32 v173, v47, v173
	s_waitcnt lgkmcnt(1)
	v_add_f32_e32 v174, v64, v174
	v_add_f32_e32 v175, v65, v175
	s_waitcnt lgkmcnt(0)
	v_add_f32_e32 v176, v48, v176
	v_add_f32_e32 v177, v49, v177
	v_max_f32_e32 v34, v132, v136
	v_max_f32_e32 v35, v133, v137
	v_max3_f32 v36, v34, s84, v35
	v_max_f32_e32 v34, v134, v138
	v_max_f32_e32 v35, v135, v139
	v_max3_f32 v36, v36, v34, v35
	v_max_f32_e32 v34, v140, v142
	v_max_f32_e32 v35, v141, v143
	v_max3_f32 v36, v36, v34, v35
	v_max_f32_e32 v34, v144, v150
	v_max_f32_e32 v35, v145, v151
	v_max3_f32 v36, v36, v34, v35
	v_max_f32_e32 v34, v148, v152
	v_max_f32_e32 v35, v149, v153
	v_max3_f32 v36, v36, v34, v35
	v_max_f32_e32 v34, v166, v168
	v_max_f32_e32 v35, v167, v169
	v_max3_f32 v36, v36, v34, v35
	v_max_f32_e32 v34, v170, v172
	v_max_f32_e32 v35, v171, v173
	v_max3_f32 v36, v36, v34, v35
	v_max_f32_e32 v34, v174, v176
	v_max_f32_e32 v35, v175, v177
	v_max3_f32 v184, v36, v34, v35
